# loop-edge edits: scalar loop control, LUT constant load and fast-path tests hoisted above the closing barrier in both attention loops
# baseline (speedup 1.0000x reference)
; #define SBAR() __builtin_amdgcn_sched_barrier(0)
; #define NEGM(t) do { if (BIAS) { const float c_ = cinit<BIAS, VIRT>((t), qw0, lut); if (c_ != c_cur) { c_cur = c_; const float nm_ = c_ - m_reg; _Pragma("unroll") for (int r = 0; r < 16; ++r) negm[r] = nm_; } } } while (0)
; __device__ __forceinline__ void finishSM(f32x16& p0, f32x16& p1, float alpha, float& l_reg, bf16x8& pa0, bf16x8& pa1, bf16x8& pa2, bf16x8& pa3) {
; #pragma unroll
;   for (int r = 0; r < 16; ++r) p1[r] = __builtin_amdgcn_exp2f(p1[r]);
;   float ps = 0;
; #pragma unroll
;   for (int r = 0; r < 16; ++r) ps += p0[r];
; #pragma unroll
;   for (int r = 0; r < 16; ++r) ps += p1[r];
;   { auto rr = __builtin_amdgcn_permlane32_swap(__float_as_uint(ps), __float_as_uint(ps), false, false);
;     ps = __uint_as_float(rr[0]) + __uint_as_float(rr[1]); }
;   l_reg = l_reg * alpha + ps;
;     ...
;   PK4(p0, 0, pa0); PK4(p0, 8, pa1); PK4(p1, 0, pa2); PK4(p1, 8, pa3);
;     ...
; }
; template <int DQK> __device__ __forceinline__ void qkt(f32x16& p0, f32x16& p1, const char* Ks, const bf16x8* qr, int r32, int hi, const f32x16& negm) {
; #pragma unroll
;   for (int d0 = 0; d0 < DQK / 16; ++d0) { const int cb = (d0 * 16 + hi * 8) * 2;
;     const bf16x8 b0 = *reinterpret_cast<const bf16x8*>(Ks + (DQK == 128 ? KSWZ(r32, cb) : KSWZ64(r32, cb)));
;     const bf16x8 b1 = *reinterpret_cast<const bf16x8*>(Ks + (DQK == 128 ? KSWZ(32 + r32, cb) : KSWZ64(32 + r32, cb)));
;     if (d0 == 0) { p0 = __builtin_amdgcn_mfma_f32_32x32x16_bf16(b0, qr[0], negm, 0, 0, 0); p1 = __builtin_amdgcn_mfma_f32_32x32x16_bf16(b1, qr[0], negm, 0, 0, 0); }
;     else { p0 = __builtin_amdgcn_mfma_f32_32x32x16_bf16(b0, qr[d0], p0, 0, 0, 0); p1 = __builtin_amdgcn_mfma_f32_32x32x16_bf16(b1, qr[d0], p1, 0, 0, 0); } }
; }
; template <int DQK, bool BIAS, bool VIRT = false>
; __device__ __forceinline__ void attn_pass(const bf16_t* __restrict__ Qb, const bf16_t* __restrict__ Kh, const bf16_t* __restrict__ Vh, int L, int NT, int qw0, const float* lut, f32x16 (&o)[4], char* lds, int nact) {
;     ...
;     NEGM(j); SBAR(); qkt<DQK>(pB0, pB1, K_lds + SHM_K, qr, r32, hi, negm);
;     finishSM(pA0, pA1, alA, l_reg, pa0, pa1, pa2, pa3); SBAR();
.Lfast_g1:
	ds_read_b128 v[198:201], v195 offset:57344
	ds_read_b128 v[202:205], v195 offset:49152
	ds_read_b128 v[244:247], v211 offset:57344
	ds_read_b128 v[206:209], v211 offset:49152
	v_add_f32_e32 v227, 0, v238
	v_add_f32_e32 v227, v240, v227
	v_cvt_pk_bf16_f32 v66, v238, v240
	v_add_f32_e32 v227, v236, v227
	v_add_f32_e32 v227, v239, v227
	v_cvt_pk_bf16_f32 v67, v236, v239
	v_add_f32_e32 v227, v235, v227
	v_add_f32_e32 v227, v237, v227
	v_cvt_pk_bf16_f32 v68, v235, v237
	v_add_f32_e32 v227, v233, v227
	v_add_f32_e32 v227, v234, v227
	v_cvt_pk_bf16_f32 v69, v233, v234
	s_waitcnt lgkmcnt(3)
	v_mfma_f32_32x32x16_bf16 v[114:129], v[198:201], v[174:177], v[82:97]
	v_add_f32_e32 v227, v184, v227
	v_add_f32_e32 v227, v232, v227
	v_cvt_pk_bf16_f32 v70, v184, v232
	v_add_f32_e32 v227, v183, v227
	v_add_f32_e32 v227, v185, v227
	s_waitcnt lgkmcnt(2)
	v_mfma_f32_32x32x16_bf16 v[130:145], v[202:205], v[174:177], v[82:97]
	ds_read_b128 v[198:201], v210 offset:57344
	ds_read_b128 v[202:205], v210 offset:49152
	v_cvt_pk_bf16_f32 v71, v183, v185
	v_add_f32_e32 v227, v180, v227
	v_add_f32_e32 v227, v182, v227
	v_cvt_pk_bf16_f32 v72, v180, v182
	v_add_f32_e32 v227, v179, v227
	s_waitcnt lgkmcnt(3)
	v_mfma_f32_32x32x16_bf16 v[114:129], v[244:247], v[170:173], v[114:129]
	v_add_f32_e32 v227, v181, v227
	v_cvt_pk_bf16_f32 v73, v179, v181
	v_exp_f32_e32 v98, v98
	v_exp_f32_e32 v99, v99
	v_permlane32_swap_b32_e32 v66, v68
	s_waitcnt lgkmcnt(2)
	v_mfma_f32_32x32x16_bf16 v[130:145], v[206:209], v[170:173], v[130:145]
	ds_read_b128 v[244:247], v197 offset:57344
	ds_read_b128 v[206:209], v197 offset:49152
	v_permlane32_swap_b32_e32 v67, v69
	v_permlane32_swap_b32_e32 v70, v72
	v_permlane32_swap_b32_e32 v71, v73
	v_exp_f32_e32 v100, v100
	v_add_f32_e32 v227, v98, v227
	s_waitcnt lgkmcnt(3)
	v_mfma_f32_32x32x16_bf16 v[114:129], v[198:201], v[166:169], v[114:129]
	v_exp_f32_e32 v101, v101
	v_add_f32_e32 v227, v99, v227
	v_exp_f32_e32 v102, v102
	v_add_f32_e32 v227, v100, v227
	v_exp_f32_e32 v103, v103
	s_waitcnt lgkmcnt(2)
	v_mfma_f32_32x32x16_bf16 v[130:145], v[202:205], v[166:169], v[130:145]
	ds_read_b128 v[198:201], v196 offset:57344
	ds_read_b128 v[202:205], v196 offset:49152
	v_add_f32_e32 v227, v101, v227
	v_exp_f32_e32 v104, v104
	v_add_f32_e32 v227, v102, v227
	v_exp_f32_e32 v105, v105
	s_waitcnt lgkmcnt(3)
	v_mfma_f32_32x32x16_bf16 v[114:129], v[244:247], v[162:165], v[114:129]
	v_add_f32_e32 v227, v103, v227
	v_exp_f32_e32 v106, v106
	v_add_f32_e32 v227, v104, v227
	v_exp_f32_e32 v107, v107
	s_waitcnt lgkmcnt(2)
	v_mfma_f32_32x32x16_bf16 v[130:145], v[206:209], v[162:165], v[130:145]
	ds_read_b128 v[244:247], v222 offset:57344
	ds_read_b128 v[206:209], v222 offset:49152
	v_add_f32_e32 v227, v105, v227
	v_exp_f32_e32 v108, v108
	v_add_f32_e32 v227, v106, v227
	v_exp_f32_e32 v109, v109
	s_waitcnt lgkmcnt(3)
	v_mfma_f32_32x32x16_bf16 v[114:129], v[198:201], v[158:161], v[114:129]
	v_add_f32_e32 v227, v107, v227
	v_exp_f32_e32 v110, v110
	v_add_f32_e32 v227, v108, v227
	v_exp_f32_e32 v111, v111
	s_waitcnt lgkmcnt(2)
	v_mfma_f32_32x32x16_bf16 v[130:145], v[202:205], v[158:161], v[130:145]
	ds_read_b128 v[198:201], v223 offset:57344
	ds_read_b128 v[202:205], v223 offset:49152
	v_add_f32_e32 v227, v109, v227
	v_exp_f32_e32 v112, v112
	v_add_f32_e32 v227, v110, v227
	v_exp_f32_e32 v113, v113
	s_waitcnt lgkmcnt(3)
	v_mfma_f32_32x32x16_bf16 v[114:129], v[244:247], v[154:157], v[114:129]
	v_add_f32_e32 v227, v111, v227
	v_add_f32_e32 v227, v112, v227
	v_add_f32_e32 v227, v113, v227
	v_mov_b32_e32 v228, v227
	s_waitcnt lgkmcnt(2)
	v_mfma_f32_32x32x16_bf16 v[130:145], v[206:209], v[154:157], v[130:145]
	ds_read_b128 v[244:247], v224 offset:57344
	ds_read_b128 v[206:209], v224 offset:49152
	v_cvt_pk_bf16_f32 v74, v98, v99
	v_cvt_pk_bf16_f32 v75, v100, v101
	v_cvt_pk_bf16_f32 v76, v102, v103
	v_cvt_pk_bf16_f32 v77, v104, v105
	s_waitcnt lgkmcnt(3)
	v_mfma_f32_32x32x16_bf16 v[114:129], v[198:201], v[150:153], v[114:129]
	v_cvt_pk_bf16_f32 v78, v106, v107
	v_cvt_pk_bf16_f32 v79, v108, v109
	v_cvt_pk_bf16_f32 v80, v110, v111
	v_cvt_pk_bf16_f32 v81, v112, v113
	s_waitcnt lgkmcnt(2)
; #define SBAR() __builtin_amdgcn_sched_barrier(0)
; template <bool FIRST> __device__ __forceinline__ void partialSM(f32x16& p0, f32x16& p1, float& m_reg, float& alpha, f32x16& negm, float c_cur) {
;   float pmax = p0[0];
; #pragma unroll
;   for (int r = 1; r < 16; ++r) pmax = fmaxf(pmax, p0[r]);
; #pragma unroll
;   for (int r = 0; r < 16; ++r) pmax = fmaxf(pmax, p1[r]);
;   { auto rr = __builtin_amdgcn_permlane32_swap(__float_as_uint(pmax), __float_as_uint(pmax), false, false);
;     pmax = fmaxf(__uint_as_float(rr[0]), __uint_as_float(rr[1])); }
; template <int OFF> __device__ __forceinline__ s16x4 tr_read(int vb) {
;   s16x4 r; asm volatile("ds_read_b64_tr_b16 %0, %1 offset:%2" : "=&v"(r) : "v"(vb), "i"(OFF) : "memory"); return r;
; }
; template <int D0> __device__ __forceinline__ void pv_one(f32x16& od, int vb, bf16x8 pa0, bf16x8 pa1, bf16x8 pa2, bf16x8 pa3) {
;   const s16x4 l0 = tr_read<v_rd_off(D0, 0, 0)>(vb), h0 = tr_read<v_rd_off(D0, 0, 1)>(vb), l1 = tr_read<v_rd_off(D0, 1, 0)>(vb), h1 = tr_read<v_rd_off(D0, 1, 1)>(vb);
;   const s16x4 l2 = tr_read<v_rd_off(D0, 2, 0)>(vb), h2 = tr_read<v_rd_off(D0, 2, 1)>(vb), l3 = tr_read<v_rd_off(D0, 3, 0)>(vb), h3 = tr_read<v_rd_off(D0, 3, 1)>(vb);
;   asm volatile("s_waitcnt lgkmcnt(0)" ::: "memory"); SBAR();
;     ...
;   od = __builtin_amdgcn_mfma_f32_32x32x16_bf16(pa0, PK(l0, h0), od, 0, 0, 0);
;   od = __builtin_amdgcn_mfma_f32_32x32x16_bf16(pa1, PK(l1, h1), od, 0, 0, 0);
;   od = __builtin_amdgcn_mfma_f32_32x32x16_bf16(pa2, PK(l2, h2), od, 0, 0, 0);
;   od = __builtin_amdgcn_mfma_f32_32x32x16_bf16(pa3, PK(l3, h3), od, 0, 0, 0);
;     ...
; }
; __device__ __forceinline__ void pv_d0(f32x16* o, int vb, bf16x8 pa0, bf16x8 pa1, bf16x8 pa2, bf16x8 pa3) {
;   pv_one<0>(o[0], vb, pa0, pa1, pa2, pa3); pv_one<1>(o[1], vb, pa0, pa1, pa2, pa3); pv_one<2>(o[2], vb, pa0, pa1, pa2, pa3); pv_one<3>(o[3], vb, pa0, pa1, pa2, pa3);
; }
	v_mfma_f32_32x32x16_bf16 v[130:145], v[202:205], v[150:153], v[130:145]
	ds_read_b64_tr_b16 v[178:179], v193 offset:0
	ds_read_b64_tr_b16 v[180:181], v193 offset:0x800
	ds_read_b64_tr_b16 v[182:183], v193 offset:0x200
	ds_read_b64_tr_b16 v[184:185], v193 offset:0xa00
	ds_read_b64_tr_b16 v[198:199], v193 offset:0x400
	ds_read_b64_tr_b16 v[200:201], v193 offset:0xc00
	ds_read_b64_tr_b16 v[202:203], v193 offset:0x600
	ds_read_b64_tr_b16 v[204:205], v193 offset:0xe00
	v_permlane32_swap_b32_e32 v227, v228
	v_permlane32_swap_b32_e32 v74, v76
	v_permlane32_swap_b32_e32 v75, v77
	v_permlane32_swap_b32_e32 v78, v80
	s_waitcnt lgkmcnt(9)
	v_mfma_f32_32x32x16_bf16 v[114:129], v[244:247], v[146:149], v[114:129]
	v_permlane32_swap_b32_e32 v79, v81
	v_add_co_u32_e32 v218, vcc, s77, v186
	s_nop 1
	v_addc_co_u32_e32 v219, vcc, 0, v187, vcc
	s_waitcnt lgkmcnt(8)
	v_mfma_f32_32x32x16_bf16 v[130:145], v[206:209], v[146:149], v[130:145]
	global_load_dwordx4 v[98:101], v[186:187], off offset:512
	global_load_dwordx4 v[102:105], v[186:187], off
	global_load_dwordx4 v[110:113], v[218:219], off offset:512
	global_load_dwordx4 v[106:109], v[218:219], off
	s_waitcnt lgkmcnt(6)
	v_mfma_f32_32x32x16_bf16 v[2:17], v[66:69], v[178:181], v[2:17]
	ds_read_b64_tr_b16 v[178:179], v193 offset:0x1000
	ds_read_b64_tr_b16 v[180:181], v193 offset:0x1800
	s_waitcnt lgkmcnt(6)
	v_mfma_f32_32x32x16_bf16 v[50:65], v[66:69], v[182:185], v[50:65]
	ds_read_b64_tr_b16 v[182:183], v193 offset:0x1200
	ds_read_b64_tr_b16 v[184:185], v193 offset:0x1a00
	s_waitcnt lgkmcnt(6)
	v_mfma_f32_32x32x16_bf16 v[34:49], v[66:69], v[198:201], v[34:49]
	ds_read_b64_tr_b16 v[198:199], v193 offset:0x1400
	ds_read_b64_tr_b16 v[200:201], v193 offset:0x1c00
	s_waitcnt lgkmcnt(6)
	v_mfma_f32_32x32x16_bf16 v[18:33], v[66:69], v[202:205], v[18:33]
	ds_read_b64_tr_b16 v[202:203], v193 offset:0x1600
	ds_read_b64_tr_b16 v[204:205], v193 offset:0x1e00
	s_waitcnt lgkmcnt(6)
	v_mfma_f32_32x32x16_bf16 v[2:17], v[70:73], v[178:181], v[2:17]
	ds_read_b64_tr_b16 v[178:179], v193 offset:0x2000
	ds_read_b64_tr_b16 v[180:181], v193 offset:0x2800
	v_max_f32_e32 v218, v130, v131
	v_max3_f32 v218, v218, v132, v133
	s_waitcnt lgkmcnt(6)
	v_mfma_f32_32x32x16_bf16 v[50:65], v[70:73], v[182:185], v[50:65]
	ds_read_b64_tr_b16 v[182:183], v193 offset:0x2200
	ds_read_b64_tr_b16 v[184:185], v193 offset:0x2a00
	v_max3_f32 v218, v218, v134, v135
	v_max3_f32 v218, v218, v136, v137
	s_waitcnt lgkmcnt(6)
	v_mfma_f32_32x32x16_bf16 v[34:49], v[70:73], v[198:201], v[34:49]
	ds_read_b64_tr_b16 v[198:199], v193 offset:0x2400
	ds_read_b64_tr_b16 v[200:201], v193 offset:0x2c00
	v_max3_f32 v218, v218, v138, v139
	v_max3_f32 v218, v218, v140, v141
	s_waitcnt lgkmcnt(6)
	v_mfma_f32_32x32x16_bf16 v[18:33], v[70:73], v[202:205], v[18:33]
	ds_read_b64_tr_b16 v[202:203], v193 offset:0x2600
	ds_read_b64_tr_b16 v[204:205], v193 offset:0x2e00
	v_max3_f32 v218, v218, v142, v143
	v_max3_f32 v218, v218, v144, v145
	s_waitcnt lgkmcnt(6)
	v_mfma_f32_32x32x16_bf16 v[2:17], v[74:77], v[178:181], v[2:17]
	ds_read_b64_tr_b16 v[178:179], v193 offset:0x3000
	ds_read_b64_tr_b16 v[180:181], v193 offset:0x3800
	v_max3_f32 v218, v218, v114, v115
	v_max3_f32 v218, v218, v116, v117
	s_waitcnt lgkmcnt(6)
	v_mfma_f32_32x32x16_bf16 v[50:65], v[74:77], v[182:185], v[50:65]
	ds_read_b64_tr_b16 v[182:183], v193 offset:0x3200
	ds_read_b64_tr_b16 v[184:185], v193 offset:0x3a00
	v_max3_f32 v218, v218, v118, v119
	v_max3_f32 v218, v218, v120, v121
	s_waitcnt lgkmcnt(6)
	v_mfma_f32_32x32x16_bf16 v[34:49], v[74:77], v[198:201], v[34:49]
	ds_read_b64_tr_b16 v[198:199], v193 offset:0x3400
	ds_read_b64_tr_b16 v[200:201], v193 offset:0x3c00
	v_max3_f32 v218, v218, v122, v123
	s_waitcnt lgkmcnt(6)
	v_mfma_f32_32x32x16_bf16 v[18:33], v[74:77], v[202:205], v[18:33]
	ds_read_b64_tr_b16 v[202:203], v193 offset:0x3600
	ds_read_b64_tr_b16 v[204:205], v193 offset:0x3e00
	v_max3_f32 v218, v218, v124, v125
	s_waitcnt lgkmcnt(6)
	v_mfma_f32_32x32x16_bf16 v[2:17], v[78:81], v[178:181], v[2:17]
	v_max3_f32 v218, v218, v126, v127
	s_waitcnt lgkmcnt(4)
	v_mfma_f32_32x32x16_bf16 v[50:65], v[78:81], v[182:185], v[50:65]
	v_max3_f32 v218, v218, v128, v129
	s_waitcnt lgkmcnt(2)
	v_mfma_f32_32x32x16_bf16 v[34:49], v[78:81], v[198:201], v[34:49]
	v_mov_b32_e32 v219, v218
	s_waitcnt lgkmcnt(0)
	v_mfma_f32_32x32x16_bf16 v[18:33], v[78:81], v[202:205], v[18:33]
	v_permlane32_swap_b32_e32 v218, v219
	v_max_f32_e32 v66, v218, v219
	s_branch .Ljoin_g1

; #define SBAR() __builtin_amdgcn_sched_barrier(0)
; template <bool FIRST> __device__ __forceinline__ void partialSM(f32x16& p0, f32x16& p1, float& m_reg, float& alpha, f32x16& negm, float c_cur) {
;     ...
;   for (int r = 0; r < 16; ++r) p0[r] = __builtin_amdgcn_exp2f(p0[r]);
; }
; __device__ __forceinline__ void finishSM(f32x16& p0, f32x16& p1, float alpha, float& l_reg, bf16x8& pa0, bf16x8& pa1, bf16x8& pa2, bf16x8& pa3) {
; #pragma unroll
;   for (int r = 0; r < 16; ++r) p1[r] = __builtin_amdgcn_exp2f(p1[r]);
;   float ps = 0;
; #pragma unroll
;   for (int r = 0; r < 16; ++r) ps += p0[r];
; #pragma unroll
;   for (int r = 0; r < 16; ++r) ps += p1[r];
;   { auto rr = __builtin_amdgcn_permlane32_swap(__float_as_uint(ps), __float_as_uint(ps), false, false);
;     ps = __uint_as_float(rr[0]) + __uint_as_float(rr[1]); }
;   l_reg = l_reg * alpha + ps;
;     ...
;   PK4(p0, 0, pa0); PK4(p0, 8, pa1); PK4(p1, 0, pa2); PK4(p1, 8, pa3);
;     ...
; }
; template <int DQK> __device__ __forceinline__ void qkt(f32x16& p0, f32x16& p1, const char* Ks, const bf16x8* qr, int r32, int hi, const f32x16& negm) {
; #pragma unroll
;   for (int d0 = 0; d0 < DQK / 16; ++d0) { const int cb = (d0 * 16 + hi * 8) * 2;
;     const bf16x8 b0 = *reinterpret_cast<const bf16x8*>(Ks + (DQK == 128 ? KSWZ(r32, cb) : KSWZ64(r32, cb)));
;     const bf16x8 b1 = *reinterpret_cast<const bf16x8*>(Ks + (DQK == 128 ? KSWZ(32 + r32, cb) : KSWZ64(32 + r32, cb)));
;     if (d0 == 0) { p0 = __builtin_amdgcn_mfma_f32_32x32x16_bf16(b0, qr[0], negm, 0, 0, 0); p1 = __builtin_amdgcn_mfma_f32_32x32x16_bf16(b1, qr[0], negm, 0, 0, 0); }
;     else { p0 = __builtin_amdgcn_mfma_f32_32x32x16_bf16(b0, qr[d0], p0, 0, 0, 0); p1 = __builtin_amdgcn_mfma_f32_32x32x16_bf16(b1, qr[d0], p1, 0, 0, 0); } }
; }
; template <int DQK, bool BIAS, bool VIRT = false>
; __device__ __forceinline__ void attn_pass(const bf16_t* __restrict__ Qb, const bf16_t* __restrict__ Kh, const bf16_t* __restrict__ Vh, int L, int NT, int qw0, const float* lut, f32x16 (&o)[4], char* lds, int nact) {
;     ...
;     __syncthreads(); SWAIT(); SWRITE(0, SE);
;     RESC(alB); __syncthreads();
;     NEGM(j + 1); SBAR(); qkt<DQK>(pA0, pA1, K_lds, qr, r32, hi, negm);
;     finishSM(pB0, pB1, alB, l_reg, pa0, pa1, pa2, pa3); SBAR();
.LBB0_76:
	s_add_i32 s14, s12, 0x80
	v_exp_f32_e32 v178, v130
	v_exp_f32_e32 v205, v131
	v_exp_f32_e32 v179, v132
	v_exp_f32_e32 v204, v133
	v_exp_f32_e32 v180, v134
	v_exp_f32_e32 v203, v135
	v_exp_f32_e32 v181, v136
	v_exp_f32_e32 v202, v137
	v_exp_f32_e32 v182, v138
	v_exp_f32_e32 v201, v139
	v_exp_f32_e32 v183, v140
	v_exp_f32_e32 v200, v141
	v_exp_f32_e32 v184, v142
	v_exp_f32_e32 v199, v143
	v_exp_f32_e32 v185, v144
	v_exp_f32_e32 v198, v145
	s_cmp_le_u32 s14, s16
	s_waitcnt lgkmcnt(0)
	s_barrier
	s_cbranch_scc0 .Lslow_g2
	ds_read_b128 v[232:235], v195 offset:40960
	ds_read_b128 v[236:239], v195 offset:32768
	ds_read_b128 v[244:247], v211 offset:40960
	ds_read_b128 v[240:243], v211 offset:32768
	v_add_f32_e32 v230, 0, v178
	v_add_f32_e32 v230, v205, v230
	v_cvt_pk_bf16_f32 v178, v178, v205
	v_add_f32_e32 v230, v179, v230
	v_add_f32_e32 v230, v204, v230
	v_cvt_pk_bf16_f32 v179, v179, v204
	v_add_f32_e32 v230, v180, v230
	v_add_f32_e32 v230, v203, v230
	v_cvt_pk_bf16_f32 v180, v180, v203
	v_add_f32_e32 v230, v181, v230
	v_add_f32_e32 v230, v202, v230
	v_cvt_pk_bf16_f32 v181, v181, v202
	s_waitcnt lgkmcnt(3)
	v_mfma_f32_32x32x16_bf16 v[98:113], v[232:235], v[174:177], v[82:97]
	v_add_f32_e32 v230, v182, v230
	v_add_f32_e32 v230, v201, v230
	v_cvt_pk_bf16_f32 v182, v182, v201
	v_add_f32_e32 v230, v183, v230
	v_add_f32_e32 v230, v200, v230
	s_waitcnt lgkmcnt(2)
	v_mfma_f32_32x32x16_bf16 v[130:145], v[236:239], v[174:177], v[82:97]
	ds_read_b128 v[232:235], v210 offset:40960
	ds_read_b128 v[236:239], v210 offset:32768
	v_cvt_pk_bf16_f32 v183, v183, v200
	v_add_f32_e32 v230, v184, v230
	v_add_f32_e32 v230, v199, v230
	v_cvt_pk_bf16_f32 v184, v184, v199
	v_add_f32_e32 v230, v185, v230
	s_waitcnt lgkmcnt(3)
	v_mfma_f32_32x32x16_bf16 v[98:113], v[244:247], v[170:173], v[98:113]
	v_add_f32_e32 v230, v198, v230
	v_cvt_pk_bf16_f32 v185, v185, v198
	v_exp_f32_e32 v114, v114
	v_exp_f32_e32 v115, v115
	v_permlane32_swap_b32_e32 v178, v180
	s_waitcnt lgkmcnt(2)
	v_mfma_f32_32x32x16_bf16 v[130:145], v[240:243], v[170:173], v[130:145]
	ds_read_b128 v[244:247], v197 offset:40960
	ds_read_b128 v[240:243], v197 offset:32768
	v_permlane32_swap_b32_e32 v179, v181
	v_permlane32_swap_b32_e32 v182, v184
	v_permlane32_swap_b32_e32 v183, v185
	v_exp_f32_e32 v116, v116
	v_add_f32_e32 v230, v114, v230
	s_waitcnt lgkmcnt(3)
	v_mfma_f32_32x32x16_bf16 v[98:113], v[232:235], v[166:169], v[98:113]
	v_exp_f32_e32 v117, v117
	v_add_f32_e32 v230, v115, v230
	v_exp_f32_e32 v118, v118
	v_add_f32_e32 v230, v116, v230
	v_exp_f32_e32 v119, v119
	s_waitcnt lgkmcnt(2)
	v_mfma_f32_32x32x16_bf16 v[130:145], v[236:239], v[166:169], v[130:145]
	ds_read_b128 v[232:235], v196 offset:40960
	ds_read_b128 v[236:239], v196 offset:32768
	v_add_f32_e32 v230, v117, v230
	v_exp_f32_e32 v120, v120
	v_add_f32_e32 v230, v118, v230
	v_exp_f32_e32 v121, v121
	s_waitcnt lgkmcnt(3)
	v_mfma_f32_32x32x16_bf16 v[98:113], v[244:247], v[162:165], v[98:113]
	v_add_f32_e32 v230, v119, v230
	v_exp_f32_e32 v122, v122
	v_add_f32_e32 v230, v120, v230
	v_exp_f32_e32 v123, v123
	s_waitcnt lgkmcnt(2)
	v_mfma_f32_32x32x16_bf16 v[130:145], v[240:243], v[162:165], v[130:145]
	ds_read_b128 v[244:247], v222 offset:40960
	ds_read_b128 v[240:243], v222 offset:32768
	v_add_f32_e32 v230, v121, v230
	v_exp_f32_e32 v124, v124
	v_add_f32_e32 v230, v122, v230
	v_exp_f32_e32 v125, v125
	s_waitcnt lgkmcnt(3)
	v_mfma_f32_32x32x16_bf16 v[98:113], v[232:235], v[158:161], v[98:113]
	v_add_f32_e32 v230, v123, v230
	v_exp_f32_e32 v126, v126
	v_add_f32_e32 v230, v124, v230
	v_exp_f32_e32 v127, v127
	s_waitcnt lgkmcnt(2)
	v_mfma_f32_32x32x16_bf16 v[130:145], v[236:239], v[158:161], v[130:145]
	ds_read_b128 v[232:235], v223 offset:40960
	ds_read_b128 v[236:239], v223 offset:32768
	v_add_f32_e32 v230, v125, v230
	v_exp_f32_e32 v128, v128
	v_add_f32_e32 v230, v126, v230
	v_exp_f32_e32 v129, v129
	s_waitcnt lgkmcnt(3)
	v_mfma_f32_32x32x16_bf16 v[98:113], v[244:247], v[154:157], v[98:113]
	v_add_f32_e32 v230, v127, v230
	v_add_f32_e32 v230, v128, v230
	v_add_f32_e32 v230, v129, v230
	v_mov_b32_e32 v231, v230
	s_waitcnt lgkmcnt(2)
	v_mfma_f32_32x32x16_bf16 v[130:145], v[240:243], v[154:157], v[130:145]
	ds_read_b128 v[244:247], v224 offset:40960
	ds_read_b128 v[240:243], v224 offset:32768
	v_cvt_pk_bf16_f32 v198, v114, v115
	v_cvt_pk_bf16_f32 v199, v116, v117
	v_cvt_pk_bf16_f32 v200, v118, v119
	v_cvt_pk_bf16_f32 v201, v120, v121
	s_waitcnt lgkmcnt(3)
	v_mfma_f32_32x32x16_bf16 v[98:113], v[232:235], v[150:153], v[98:113]
	v_cvt_pk_bf16_f32 v202, v122, v123
	v_cvt_pk_bf16_f32 v203, v124, v125
	v_cvt_pk_bf16_f32 v204, v126, v127
	v_cvt_pk_bf16_f32 v205, v128, v129
	s_waitcnt lgkmcnt(2)
; #define SBAR() __builtin_amdgcn_sched_barrier(0)
; template <bool FIRST> __device__ __forceinline__ void partialSM(f32x16& p0, f32x16& p1, float& m_reg, float& alpha, f32x16& negm, float c_cur) {
;   float pmax = p0[0];
; #pragma unroll
;   for (int r = 1; r < 16; ++r) pmax = fmaxf(pmax, p0[r]);
; #pragma unroll
;   for (int r = 0; r < 16; ++r) pmax = fmaxf(pmax, p1[r]);
;   { auto rr = __builtin_amdgcn_permlane32_swap(__float_as_uint(pmax), __float_as_uint(pmax), false, false);
;     pmax = fmaxf(__uint_as_float(rr[0]), __uint_as_float(rr[1])); }
; template <int OFF> __device__ __forceinline__ s16x4 tr_read(int vb) {
;   s16x4 r; asm volatile("ds_read_b64_tr_b16 %0, %1 offset:%2" : "=&v"(r) : "v"(vb), "i"(OFF) : "memory"); return r;
; }
; template <int D0> __device__ __forceinline__ void pv_one(f32x16& od, int vb, bf16x8 pa0, bf16x8 pa1, bf16x8 pa2, bf16x8 pa3) {
;   const s16x4 l0 = tr_read<v_rd_off(D0, 0, 0)>(vb), h0 = tr_read<v_rd_off(D0, 0, 1)>(vb), l1 = tr_read<v_rd_off(D0, 1, 0)>(vb), h1 = tr_read<v_rd_off(D0, 1, 1)>(vb);
;   const s16x4 l2 = tr_read<v_rd_off(D0, 2, 0)>(vb), h2 = tr_read<v_rd_off(D0, 2, 1)>(vb), l3 = tr_read<v_rd_off(D0, 3, 0)>(vb), h3 = tr_read<v_rd_off(D0, 3, 1)>(vb);
;   asm volatile("s_waitcnt lgkmcnt(0)" ::: "memory"); SBAR();
;     ...
;   od = __builtin_amdgcn_mfma_f32_32x32x16_bf16(pa0, PK(l0, h0), od, 0, 0, 0);
;   od = __builtin_amdgcn_mfma_f32_32x32x16_bf16(pa1, PK(l1, h1), od, 0, 0, 0);
;   od = __builtin_amdgcn_mfma_f32_32x32x16_bf16(pa2, PK(l2, h2), od, 0, 0, 0);
;   od = __builtin_amdgcn_mfma_f32_32x32x16_bf16(pa3, PK(l3, h3), od, 0, 0, 0);
;     ...
; }
; __device__ __forceinline__ void pv_d0(f32x16* o, int vb, bf16x8 pa0, bf16x8 pa1, bf16x8 pa2, bf16x8 pa3) {
;   pv_one<0>(o[0], vb, pa0, pa1, pa2, pa3); pv_one<1>(o[1], vb, pa0, pa1, pa2, pa3); pv_one<2>(o[2], vb, pa0, pa1, pa2, pa3); pv_one<3>(o[3], vb, pa0, pa1, pa2, pa3);
; }
	v_mfma_f32_32x32x16_bf16 v[130:145], v[236:239], v[150:153], v[130:145]
	ds_read_b64_tr_b16 v[206:207], v190 offset:0
	ds_read_b64_tr_b16 v[208:209], v190 offset:0x800
	ds_read_b64_tr_b16 v[232:233], v190 offset:0x200
	ds_read_b64_tr_b16 v[234:235], v190 offset:0xa00
	ds_read_b64_tr_b16 v[236:237], v190 offset:0x400
	ds_read_b64_tr_b16 v[238:239], v190 offset:0xc00
	v_permlane32_swap_b32_e32 v230, v231
	v_permlane32_swap_b32_e32 v198, v200
	v_permlane32_swap_b32_e32 v199, v201
	v_permlane32_swap_b32_e32 v202, v204
	s_waitcnt lgkmcnt(7)
	v_mfma_f32_32x32x16_bf16 v[98:113], v[244:247], v[146:149], v[98:113]
	v_permlane32_swap_b32_e32 v203, v205
	v_add_co_u32_e32 v218, vcc, s80, v186
	s_nop 1
	v_addc_co_u32_e32 v219, vcc, 0, v187, vcc
	s_waitcnt lgkmcnt(6)
	v_mfma_f32_32x32x16_bf16 v[130:145], v[240:243], v[146:149], v[130:145]
	ds_read_b64_tr_b16 v[240:241], v190 offset:0x600
	ds_read_b64_tr_b16 v[242:243], v190 offset:0xe00
	global_load_dwordx4 v[114:117], v[218:219], off offset:512
	global_load_dwordx4 v[118:121], v[218:219], off
	s_waitcnt lgkmcnt(6)
	v_mfma_f32_32x32x16_bf16 v[2:17], v[178:181], v[206:209], v[2:17]
	ds_read_b64_tr_b16 v[206:207], v190 offset:0x1000
	ds_read_b64_tr_b16 v[208:209], v190 offset:0x1800
	v_add_co_u32_e32 v218, vcc, s81, v186
	s_nop 1
	v_addc_co_u32_e32 v219, vcc, 0, v187, vcc
	global_load_dwordx4 v[126:129], v[218:219], off offset:512
	global_load_dwordx4 v[122:125], v[218:219], off
	s_waitcnt lgkmcnt(6)
	v_mfma_f32_32x32x16_bf16 v[50:65], v[178:181], v[232:235], v[50:65]
	ds_read_b64_tr_b16 v[232:233], v190 offset:0x1200
	ds_read_b64_tr_b16 v[234:235], v190 offset:0x1a00
	s_waitcnt lgkmcnt(6)
	v_mfma_f32_32x32x16_bf16 v[34:49], v[178:181], v[236:239], v[34:49]
	ds_read_b64_tr_b16 v[236:237], v190 offset:0x1400
	ds_read_b64_tr_b16 v[238:239], v190 offset:0x1c00
	s_waitcnt lgkmcnt(6)
	v_mfma_f32_32x32x16_bf16 v[18:33], v[178:181], v[240:243], v[18:33]
	ds_read_b64_tr_b16 v[240:241], v190 offset:0x1600
	ds_read_b64_tr_b16 v[242:243], v190 offset:0x1e00
	s_waitcnt lgkmcnt(6)
	v_mfma_f32_32x32x16_bf16 v[2:17], v[182:185], v[206:209], v[2:17]
	ds_read_b64_tr_b16 v[206:207], v190 offset:0x2000
	ds_read_b64_tr_b16 v[208:209], v190 offset:0x2800
	v_max_f32_e32 v218, v130, v131
	v_max3_f32 v218, v218, v132, v133
	s_waitcnt lgkmcnt(6)
	v_mfma_f32_32x32x16_bf16 v[50:65], v[182:185], v[232:235], v[50:65]
	ds_read_b64_tr_b16 v[232:233], v190 offset:0x2200
	ds_read_b64_tr_b16 v[234:235], v190 offset:0x2a00
	v_max3_f32 v218, v218, v134, v135
	v_max3_f32 v218, v218, v136, v137
	s_waitcnt lgkmcnt(6)
	v_mfma_f32_32x32x16_bf16 v[34:49], v[182:185], v[236:239], v[34:49]
	ds_read_b64_tr_b16 v[236:237], v190 offset:0x2400
	ds_read_b64_tr_b16 v[238:239], v190 offset:0x2c00
	v_max3_f32 v218, v218, v138, v139
	v_max3_f32 v218, v218, v140, v141
	s_waitcnt lgkmcnt(6)
	v_mfma_f32_32x32x16_bf16 v[18:33], v[182:185], v[240:243], v[18:33]
	ds_read_b64_tr_b16 v[240:241], v190 offset:0x2600
	ds_read_b64_tr_b16 v[242:243], v190 offset:0x2e00
	v_max3_f32 v218, v218, v142, v143
	v_max3_f32 v218, v218, v144, v145
	s_waitcnt lgkmcnt(6)
	v_mfma_f32_32x32x16_bf16 v[2:17], v[198:201], v[206:209], v[2:17]
	ds_read_b64_tr_b16 v[206:207], v190 offset:0x3000
	ds_read_b64_tr_b16 v[208:209], v190 offset:0x3800
	v_max3_f32 v218, v218, v98, v99
	v_max3_f32 v218, v218, v100, v101
	s_waitcnt lgkmcnt(6)
	v_mfma_f32_32x32x16_bf16 v[50:65], v[198:201], v[232:235], v[50:65]
	ds_read_b64_tr_b16 v[232:233], v190 offset:0x3200
	ds_read_b64_tr_b16 v[234:235], v190 offset:0x3a00
	v_max3_f32 v218, v218, v102, v103
	v_max3_f32 v218, v218, v104, v105
	s_waitcnt lgkmcnt(6)
	v_mfma_f32_32x32x16_bf16 v[34:49], v[198:201], v[236:239], v[34:49]
	ds_read_b64_tr_b16 v[236:237], v190 offset:0x3400
	ds_read_b64_tr_b16 v[238:239], v190 offset:0x3c00
	v_max3_f32 v218, v218, v106, v107
	s_waitcnt lgkmcnt(6)
	v_mfma_f32_32x32x16_bf16 v[18:33], v[198:201], v[240:243], v[18:33]
	ds_read_b64_tr_b16 v[240:241], v190 offset:0x3600
	ds_read_b64_tr_b16 v[242:243], v190 offset:0x3e00
	v_max3_f32 v218, v218, v108, v109
	s_waitcnt lgkmcnt(6)
	v_mfma_f32_32x32x16_bf16 v[2:17], v[202:205], v[206:209], v[2:17]
	v_max3_f32 v218, v218, v110, v111
	s_waitcnt lgkmcnt(4)
	v_mfma_f32_32x32x16_bf16 v[50:65], v[202:205], v[232:235], v[50:65]
	v_max3_f32 v218, v218, v112, v113
	s_waitcnt lgkmcnt(2)
	v_mfma_f32_32x32x16_bf16 v[34:49], v[202:205], v[236:239], v[34:49]
	v_mov_b32_e32 v219, v218
	s_waitcnt lgkmcnt(0)
	v_mfma_f32_32x32x16_bf16 v[18:33], v[202:205], v[240:243], v[18:33]
	v_permlane32_swap_b32_e32 v218, v219
	v_max_f32_e32 v179, v218, v219
	s_branch .Ljoin_g2

; #define SBAR() __builtin_amdgcn_sched_barrier(0)
; #define SLOAD(i, k0) do { sr_[i].vs0 = GLD8(&Vh[(long)((k0) + sr) * LD + sc]); sr_[i].vs1 = GLD8(&Vh[(long)((k0) + 32 + sr) * LD + sc]); \
;     if (DQK == 128) { sr_[i].ks0 = GLD8(&Kh[(long)((k0) + sr) * LD + sc]); sr_[i].ks1 = GLD8(&Kh[(long)((k0) + 32 + sr) * LD + sc]); } \
;     else { sr_[i].ks0 = GLD8(&Kh[(long)((k0) + kr) * LD + kc]); } } while (0)
; #define SWRITE(b, i) do { *(bf16x8*)(V_lds + (b) * SHM_V + vst0) = sr_[i].vs0; *(bf16x8*)(V_lds + (b) * SHM_V + vst1) = sr_[i].vs1; \
;     if (DQK == 128) { *(bf16x8*)(K_lds + (b) * SHM_K + KSWZ(sr, sc * 2)) = sr_[i].ks0; *(bf16x8*)(K_lds + (b) * SHM_K + KSWZ(32 + sr, sc * 2)) = sr_[i].ks1; } \
;     else { *(bf16x8*)(K_lds + (b) * SHM_K + KSWZ64(kr, kc * 2)) = sr_[i].ks0; } } while (0)
; #define SWAIT() do { if (SDEPTH == 1) asm volatile("s_waitcnt vmcnt(0)" ::: "memory"); else if (DQK == 128) asm volatile("s_waitcnt vmcnt(4)" ::: "memory"); else asm volatile("s_waitcnt vmcnt(3)" ::: "memory"); } while (0)
; template <int DQK, bool BIAS, bool VIRT = false>
; __device__ __forceinline__ void attn_pass(const bf16_t* __restrict__ Qb, const bf16_t* __restrict__ Kh, const bf16_t* __restrict__ Vh, int L, int NT, int qw0, const float* lut, f32x16 (&o)[4], char* lds, int nact) {
;     ...
;   for (int j = 1; j + 1 < NT; j += 2) {
;     NEGM(j); SBAR(); qkt<DQK>(pB0, pB1, K_lds + SHM_K, qr, r32, hi, negm);
;     finishSM(pA0, pA1, alA, l_reg, pa0, pa1, pa2, pa3); SBAR();
;     SLOAD(SO, (j + SDEPTH) * KVBLK); SBAR();
;     pv_d0(o, vb0, pa0, pa1, pa2, pa3); fixup<BIAS, VIRT>(pB0, pB1, j, L, qw0, r32, hi, lut); partialSM<false>(pB0, pB1, m_reg, alB, negm, c_cur);
;     __syncthreads(); SWAIT(); SWRITE(0, SE);
;     RESC(alB); __syncthreads();
;     NEGM(j + 1); SBAR(); qkt<DQK>(pA0, pA1, K_lds, qr, r32, hi, negm);
;     finishSM(pB0, pB1, alB, l_reg, pa0, pa1, pa2, pa3); SBAR();
;     if (SDEPTH == 1 || j + 3 < NT) SLOAD(SE, (j + 1 + SDEPTH) * KVBLK); SBAR();
;     pv_d0(o, vb0 + SHM_V, pa0, pa1, pa2, pa3); fixup<BIAS, VIRT>(pA0, pA1, j + 1, L, qw0, r32, hi, lut); partialSM<false>(pA0, pA1, m_reg, alA, negm, c_cur);
;     __syncthreads(); SWAIT(); SWRITE(1, SO);
;     RESC(alA); __syncthreads();
.LBB0_82:
	v_exp_f32_e32 v238, v130
	v_exp_f32_e32 v240, v131
	v_exp_f32_e32 v236, v132
	v_exp_f32_e32 v239, v133
	v_exp_f32_e32 v235, v134
	v_exp_f32_e32 v237, v135
	v_exp_f32_e32 v233, v136
	v_exp_f32_e32 v234, v137
	v_exp_f32_e32 v184, v138
	v_exp_f32_e32 v232, v139
	v_exp_f32_e32 v183, v140
	v_exp_f32_e32 v185, v141
	v_exp_f32_e32 v180, v142
	v_exp_f32_e32 v182, v143
	v_exp_f32_e32 v179, v144
	v_exp_f32_e32 v181, v145
	v_add_f32_e32 v114, v227, v228
	v_fmac_f32_e32 v114, v226, v189
	v_add_f32_e32 v189, v230, v231
	s_add_i32 s28, s28, 2
	v_fmac_f32_e32 v189, v114, v229
	v_lshl_add_u64 v[186:187], v[186:187], 0, s[34:35]
	s_cmp_ge_u32 s28, s46
	s_cbranch_scc1 .Lpre_exit_g
	s_mov_b32 s12, s14
	v_mov_b32_e32 v226, v178
	s_add_i32 s99, s12, 64
	s_cmp_le_u32 s99, s16
	s_waitcnt lgkmcnt(0)
	s_barrier
	s_cbranch_scc1 .Lfast_g1
	s_branch .Lslow_g1
.Lpre_exit_g:
	s_waitcnt lgkmcnt(0)
	s_barrier
	s_branch .Lexit_fix128

; #define SBAR() __builtin_amdgcn_sched_barrier(0)
; #define SLOAD(i, k0) do { sr_[i].vs0 = GLD8(&Vh[(long)((k0) + sr) * LD + sc]); sr_[i].vs1 = GLD8(&Vh[(long)((k0) + 32 + sr) * LD + sc]); \
;     if (DQK == 128) { sr_[i].ks0 = GLD8(&Kh[(long)((k0) + sr) * LD + sc]); sr_[i].ks1 = GLD8(&Kh[(long)((k0) + 32 + sr) * LD + sc]); } \
;     else { sr_[i].ks0 = GLD8(&Kh[(long)((k0) + kr) * LD + kc]); } } while (0)
; #define SWRITE(b, i) do { *(bf16x8*)(V_lds + (b) * SHM_V + vst0) = sr_[i].vs0; *(bf16x8*)(V_lds + (b) * SHM_V + vst1) = sr_[i].vs1; \
;     if (DQK == 128) { *(bf16x8*)(K_lds + (b) * SHM_K + KSWZ(sr, sc * 2)) = sr_[i].ks0; *(bf16x8*)(K_lds + (b) * SHM_K + KSWZ(32 + sr, sc * 2)) = sr_[i].ks1; } \
;     else { *(bf16x8*)(K_lds + (b) * SHM_K + KSWZ64(kr, kc * 2)) = sr_[i].ks0; } } while (0)
; __device__ __forceinline__ void finishSM(f32x16& p0, f32x16& p1, float alpha, float& l_reg, bf16x8& pa0, bf16x8& pa1, bf16x8& pa2, bf16x8& pa3) {
; #pragma unroll
;   for (int r = 0; r < 16; ++r) p1[r] = __builtin_amdgcn_exp2f(p1[r]);
;   float ps = 0;
; #pragma unroll
;   for (int r = 0; r < 16; ++r) ps += p0[r];
; #pragma unroll
;   for (int r = 0; r < 16; ++r) ps += p1[r];
;   { auto rr = __builtin_amdgcn_permlane32_swap(__float_as_uint(ps), __float_as_uint(ps), false, false);
;     ps = __uint_as_float(rr[0]) + __uint_as_float(rr[1]); }
;   l_reg = l_reg * alpha + ps;
;     ...
;   PK4(p0, 0, pa0); PK4(p0, 8, pa1); PK4(p1, 0, pa2); PK4(p1, 8, pa3);
; template <int DQK, bool BIAS, bool VIRT = false>
; __device__ __forceinline__ void attn_pass(const bf16_t* __restrict__ Qb, const bf16_t* __restrict__ Kh, const bf16_t* __restrict__ Vh, int L, int NT, int qw0, const float* lut, f32x16 (&o)[4], char* lds, int nact) {
;     ...
;   SLOAD(SE, 0); asm volatile("s_waitcnt vmcnt(0)" ::: "memory"); SWRITE(0, SE); __syncthreads();
;   qkt<DQK>(pA0, pA1, K_lds, qr, r32, hi, negm); fixup<BIAS, VIRT>(pA0, pA1, 0, L, qw0, r32, hi, lut); partialSM<true>(pA0, pA1, m_reg, alA, negm, c_cur);
;   SLOAD(SO, KVBLK); if (SDEPTH == 2) { if (2 < NT) SLOAD(SE, 2 * KVBLK); }
;   SWAIT(); SWRITE(1, SO); __syncthreads();
;   for (int j = 1; j + 1 < NT; j += 2) {
;     NEGM(j); SBAR(); qkt<DQK>(pB0, pB1, K_lds + SHM_K, qr, r32, hi, negm);
.Lfast_h1:
	ds_read_b128 v[180:183], v225 offset:53248
	ds_read_b128 v[116:119], v225 offset:49152
	ds_read_b128 v[184:187], v227 offset:53248
	ds_read_b128 v[68:71], v227 offset:49152
	ds_read_b128 v[72:75], v228 offset:53248
	ds_read_b128 v[206:209], v228 offset:49152
	v_add_f32_e32 v0, 0, v148
	v_add_f32_e32 v0, v178, v0
	v_add_f32_e32 v0, v146, v0
	v_add_f32_e32 v0, v149, v0
	v_add_f32_e32 v0, v144, v0
	v_add_f32_e32 v0, v147, v0
	v_add_f32_e32 v0, v143, v0
	v_add_f32_e32 v0, v145, v0
	v_add_f32_e32 v0, v137, v0
	v_add_f32_e32 v0, v139, v0
	v_add_f32_e32 v0, v136, v0
	v_add_f32_e32 v0, v138, v0
	v_add_f32_e32 v0, v135, v0
	v_add_f32_e32 v0, v142, v0
	v_add_f32_e32 v0, v140, v0
	v_add_f32_e32 v0, v141, v0
	v_cvt_pk_bf16_f32 v76, v148, v178
	v_cvt_pk_bf16_f32 v77, v146, v149
	v_cvt_pk_bf16_f32 v78, v144, v147
	v_cvt_pk_bf16_f32 v79, v143, v145
	v_cvt_pk_bf16_f32 v80, v137, v139
	v_cvt_pk_bf16_f32 v81, v136, v138
	v_cvt_pk_bf16_f32 v82, v135, v142
	v_cvt_pk_bf16_f32 v83, v140, v141
	s_waitcnt lgkmcnt(6)
	v_cmp_neq_f32_e32 vcc, v133, v66
	s_cbranch_vccnz .Lcupd_f1

; #define SBAR() __builtin_amdgcn_sched_barrier(0)
; #define SWRITE(b, i) do { *(bf16x8*)(V_lds + (b) * SHM_V + vst0) = sr_[i].vs0; *(bf16x8*)(V_lds + (b) * SHM_V + vst1) = sr_[i].vs1; \
;     if (DQK == 128) { *(bf16x8*)(K_lds + (b) * SHM_K + KSWZ(sr, sc * 2)) = sr_[i].ks0; *(bf16x8*)(K_lds + (b) * SHM_K + KSWZ(32 + sr, sc * 2)) = sr_[i].ks1; } \
;     else { *(bf16x8*)(K_lds + (b) * SHM_K + KSWZ64(kr, kc * 2)) = sr_[i].ks0; } } while (0)
; #define SWAIT() do { if (SDEPTH == 1) asm volatile("s_waitcnt vmcnt(0)" ::: "memory"); else if (DQK == 128) asm volatile("s_waitcnt vmcnt(4)" ::: "memory"); else asm volatile("s_waitcnt vmcnt(3)" ::: "memory"); } while (0)
; template <bool BIAS, bool VIRT> __device__ __forceinline__ void fixup(f32x16& p0, f32x16& p1, int t, int L, int qw0, int r32, int hi, const float* lut) {
;   const int k0 = KVBLK * t;
;   if (BIAS) {
;     const int lo = k0 - (qw0 + (VIRT ? 15 : 31)), hi_ = k0 + 63 - qw0;
;     if (!(lo >= 128 || hi_ <= -128)) {
;       const float* lb = lut + (k0 - (qw0 + (VIRT ? (r32 & 15) : r32)) + LUTC + 4 * hi);
; #pragma unroll
;       for (int r = 0; r < 16; ++r) { const int kv = (r & 3) + 8 * (r >> 2); p0[r] += lb[kv]; p1[r] += lb[kv + 32]; }
;     }
;   }
;   if (__builtin_expect(k0 + KVBLK > L, 0)) {
;     asm volatile("" ::: "memory");
;     const int kb = k0 + 4 * hi;
; #pragma unroll
;     for (int r = 0; r < 16; ++r) { const int kv = kb + (r & 3) + 8 * (r >> 2); if (kv >= L) p0[r] = -INFINITY; if (kv + 32 >= L) p1[r] = -INFINITY; }
;   }
; }
; template <bool BIAS, bool VIRT> __device__ __forceinline__ float cinit(int t, int qw0, const float* lut) {
;   if (!BIAS) return 0.f;
;   const int k0 = KVBLK * t, lo = k0 - (qw0 + (VIRT ? 15 : 31)), hi_ = k0 + 63 - qw0;
;   return lo >= 128 ? lut[LUTN - 1] : (hi_ <= -128 ? lut[0] : 0.f);
; }
; template <int DQK, bool BIAS, bool VIRT = false>
; __device__ __forceinline__ void attn_pass(const bf16_t* __restrict__ Qb, const bf16_t* __restrict__ Kh, const bf16_t* __restrict__ Vh, int L, int NT, int qw0, const float* lut, f32x16 (&o)[4], char* lds, int nact) {
;     ...
;     __syncthreads(); SWAIT(); SWRITE(0, SE);
;     RESC(alB); __syncthreads();
;     NEGM(j + 1); SBAR(); qkt<DQK>(pA0, pA1, K_lds, qr, r32, hi, negm);
.LBB0_229:
	v_exp_f32_e32 v219, v84
	v_exp_f32_e32 v233, v85
	v_exp_f32_e32 v209, v86
	v_exp_f32_e32 v220, v87
	v_exp_f32_e32 v207, v88
	v_exp_f32_e32 v218, v89
	v_exp_f32_e32 v206, v90
	v_exp_f32_e32 v208, v91
	v_exp_f32_e32 v203, v92
	v_exp_f32_e32 v205, v93
	v_exp_f32_e32 v201, v94
	v_exp_f32_e32 v204, v95
	v_exp_f32_e32 v199, v96
	v_exp_f32_e32 v202, v97
	v_exp_f32_e32 v198, v98
	v_exp_f32_e32 v200, v99
	s_add_i32 s4, s19, 33
	s_cmpk_lt_i32 s4, 0x80
	s_cselect_b32 s100, s38, s39
	v_mov_b32_e32 v68, s100
	ds_read_b32 v133, v68
	s_add_i32 s99, s19, 0xffffffa1
	s_cmp_lt_u32 s99, 0xfffffea3
	s_cselect_b32 s99, 1, 0
	s_add_i32 s100, s18, 64
	s_cmp_le_u32 s100, s47
	s_cselect_b32 s100, 1, 0
	s_add_i32 s4, s25, -1
	s_and_b32 s99, s99, s100
	s_waitcnt lgkmcnt(0)
	s_barrier
	s_cbranch_scc1 .Lfast_h2
	s_add_i32 s4, s19, 33
	s_cmpk_lt_i32 s4, 0x80
	s_cbranch_scc0 .LBB0_233
	s_add_i32 s4, s19, 64
	s_cmpk_gt_i32 s4, 0xff41
	v_mov_b32_e32 v133, 0
	s_cbranch_scc1 .LBB0_232
	v_mov_b32_e32 v68, s38
	ds_read_b32 v133, v68

; #define SBAR() __builtin_amdgcn_sched_barrier(0)
; #define NEGM(t) do { if (BIAS) { const float c_ = cinit<BIAS, VIRT>((t), qw0, lut); if (c_ != c_cur) { c_cur = c_; const float nm_ = c_ - m_reg; _Pragma("unroll") for (int r = 0; r < 16; ++r) negm[r] = nm_; } } } while (0)
; __device__ __forceinline__ void finishSM(f32x16& p0, f32x16& p1, float alpha, float& l_reg, bf16x8& pa0, bf16x8& pa1, bf16x8& pa2, bf16x8& pa3) {
; #pragma unroll
;   for (int r = 0; r < 16; ++r) p1[r] = __builtin_amdgcn_exp2f(p1[r]);
;   float ps = 0;
; #pragma unroll
;   for (int r = 0; r < 16; ++r) ps += p0[r];
; #pragma unroll
;   for (int r = 0; r < 16; ++r) ps += p1[r];
;   { auto rr = __builtin_amdgcn_permlane32_swap(__float_as_uint(ps), __float_as_uint(ps), false, false);
;     ps = __uint_as_float(rr[0]) + __uint_as_float(rr[1]); }
;   l_reg = l_reg * alpha + ps;
;     ...
;   PK4(p0, 0, pa0); PK4(p0, 8, pa1); PK4(p1, 0, pa2); PK4(p1, 8, pa3);
; template <int DQK, bool BIAS, bool VIRT = false>
; __device__ __forceinline__ void attn_pass(const bf16_t* __restrict__ Qb, const bf16_t* __restrict__ Kh, const bf16_t* __restrict__ Vh, int L, int NT, int qw0, const float* lut, f32x16 (&o)[4], char* lds, int nact) {
;     ...
;     NEGM(j + 1); SBAR(); qkt<DQK>(pA0, pA1, K_lds, qr, r32, hi, negm);
;     finishSM(pB0, pB1, alB, l_reg, pa0, pa1, pa2, pa3); SBAR();
.Lfast_h2:
	ds_read_b128 v[84:87], v225 offset:36864
	ds_read_b128 v[100:103], v225 offset:32768
	ds_read_b128 v[88:91], v227 offset:36864
	ds_read_b128 v[134:137], v227 offset:32768
	ds_read_b128 v[138:141], v228 offset:36864
	ds_read_b128 v[142:145], v228 offset:32768
	v_add_f32_e32 v235, 0, v219
	v_add_f32_e32 v235, v233, v235
	v_add_f32_e32 v235, v209, v235
	v_add_f32_e32 v235, v220, v235
	v_add_f32_e32 v235, v207, v235
	v_add_f32_e32 v235, v218, v235
	v_add_f32_e32 v235, v206, v235
	v_add_f32_e32 v235, v208, v235
	v_add_f32_e32 v235, v203, v235
	v_add_f32_e32 v235, v205, v235
	v_add_f32_e32 v235, v201, v235
	v_add_f32_e32 v235, v204, v235
	v_add_f32_e32 v235, v199, v235
	v_add_f32_e32 v235, v202, v235
	v_add_f32_e32 v235, v198, v235
	v_add_f32_e32 v235, v200, v235
	v_cvt_pk_bf16_f32 v92, v219, v233
	v_cvt_pk_bf16_f32 v93, v209, v220
	v_cvt_pk_bf16_f32 v94, v207, v218
	v_cvt_pk_bf16_f32 v95, v206, v208
	v_cvt_pk_bf16_f32 v96, v203, v205
	v_cvt_pk_bf16_f32 v97, v201, v204
	v_cvt_pk_bf16_f32 v98, v199, v202
	v_cvt_pk_bf16_f32 v99, v198, v200
	s_waitcnt lgkmcnt(6)
	v_cmp_neq_f32_e32 vcc, v133, v66
	s_cbranch_vccnz .Lcupd_f2

; #define SBAR() __builtin_amdgcn_sched_barrier(0)
; #define SLOAD(i, k0) do { sr_[i].vs0 = GLD8(&Vh[(long)((k0) + sr) * LD + sc]); sr_[i].vs1 = GLD8(&Vh[(long)((k0) + 32 + sr) * LD + sc]); \
;     if (DQK == 128) { sr_[i].ks0 = GLD8(&Kh[(long)((k0) + sr) * LD + sc]); sr_[i].ks1 = GLD8(&Kh[(long)((k0) + 32 + sr) * LD + sc]); } \
;     else { sr_[i].ks0 = GLD8(&Kh[(long)((k0) + kr) * LD + kc]); } } while (0)
; #define SWRITE(b, i) do { *(bf16x8*)(V_lds + (b) * SHM_V + vst0) = sr_[i].vs0; *(bf16x8*)(V_lds + (b) * SHM_V + vst1) = sr_[i].vs1; \
;     if (DQK == 128) { *(bf16x8*)(K_lds + (b) * SHM_K + KSWZ(sr, sc * 2)) = sr_[i].ks0; *(bf16x8*)(K_lds + (b) * SHM_K + KSWZ(32 + sr, sc * 2)) = sr_[i].ks1; } \
;     else { *(bf16x8*)(K_lds + (b) * SHM_K + KSWZ64(kr, kc * 2)) = sr_[i].ks0; } } while (0)
; template <bool BIAS, bool VIRT> __device__ __forceinline__ float cinit(int t, int qw0, const float* lut) {
;   if (!BIAS) return 0.f;
;   const int k0 = KVBLK * t, lo = k0 - (qw0 + (VIRT ? 15 : 31)), hi_ = k0 + 63 - qw0;
;   return lo >= 128 ? lut[LUTN - 1] : (hi_ <= -128 ? lut[0] : 0.f);
; }
; template <int DQK, bool BIAS, bool VIRT = false>
; __device__ __forceinline__ void attn_pass(const bf16_t* __restrict__ Qb, const bf16_t* __restrict__ Kh, const bf16_t* __restrict__ Vh, int L, int NT, int qw0, const float* lut, f32x16 (&o)[4], char* lds, int nact) {
;     ...
;   for (int j = 1; j + 1 < NT; j += 2) {
;     NEGM(j); SBAR(); qkt<DQK>(pB0, pB1, K_lds + SHM_K, qr, r32, hi, negm);
;     finishSM(pA0, pA1, alA, l_reg, pa0, pa1, pa2, pa3); SBAR();
;     SLOAD(SO, (j + SDEPTH) * KVBLK); SBAR();
;     pv_d0(o, vb0, pa0, pa1, pa2, pa3); fixup<BIAS, VIRT>(pB0, pB1, j, L, qw0, r32, hi, lut); partialSM<false>(pB0, pB1, m_reg, alB, negm, c_cur);
;     __syncthreads(); SWAIT(); SWRITE(0, SE);
;     RESC(alB); __syncthreads();
;     NEGM(j + 1); SBAR(); qkt<DQK>(pA0, pA1, K_lds, qr, r32, hi, negm);
;     finishSM(pB0, pB1, alB, l_reg, pa0, pa1, pa2, pa3); SBAR();
;     if (SDEPTH == 1 || j + 3 < NT) SLOAD(SE, (j + 1 + SDEPTH) * KVBLK); SBAR();
;     pv_d0(o, vb0 + SHM_V, pa0, pa1, pa2, pa3); fixup<BIAS, VIRT>(pA0, pA1, j + 1, L, qw0, r32, hi, lut); partialSM<false>(pA0, pA1, m_reg, alA, negm, c_cur);
;     __syncthreads(); SWAIT(); SWRITE(1, SO);
;     RESC(alA); __syncthreads();
.LBB0_247:
	v_exp_f32_e32 v148, v68
	v_exp_f32_e32 v178, v69
	v_exp_f32_e32 v146, v70
	v_exp_f32_e32 v149, v71
	v_exp_f32_e32 v144, v72
	v_exp_f32_e32 v147, v73
	v_exp_f32_e32 v143, v74
	v_exp_f32_e32 v145, v75
	v_exp_f32_e32 v137, v76
	v_exp_f32_e32 v139, v77
	v_exp_f32_e32 v136, v78
	v_exp_f32_e32 v138, v79
	v_exp_f32_e32 v135, v80
	v_exp_f32_e32 v142, v81
	v_exp_f32_e32 v140, v82
	v_exp_f32_e32 v141, v83
	v_add_f32_e32 v0, v0, v231
	v_fmac_f32_e32 v0, v230, v210
	v_add_f32_e32 v210, v235, v252
	s_addk_i32 s18, 0x80
	s_add_i32 s25, s25, 2
	v_fmac_f32_e32 v210, v0, v232
	v_add_u32_e32 v67, 0x200, v67
	v_lshl_add_u64 v[192:193], v[192:193], 0, s[34:35]
	v_lshl_add_u64 v[194:195], v[194:195], 0, s[34:35]
	s_cmp_ge_u32 s25, s46
	s_cbranch_scc1 .Lpre_exit_h2
	v_mov_b32_e32 v230, v133
	s_add_i32 s19, s11, s18
	s_sub_i32 s4, s19, 31
	s_cmpk_lt_i32 s4, 0x80
	s_cselect_b32 s100, s38, s39
	v_mov_b32_e32 v0, s100
	ds_read_b32 v133, v0
	s_add_i32 s99, s19, 0xffffff61
	s_cmp_lt_u32 s99, 0xfffffea3
	s_cselect_b32 s99, 1, 0
	s_cmp_le_u32 s18, s47
	s_cselect_b32 s100, 1, 0
	s_and_b32 s99, s99, s100
	s_waitcnt lgkmcnt(0)
	s_barrier
	s_cbranch_scc1 .Lfast_h1
	s_sub_i32 s4, s19, 31
	s_cmpk_lt_i32 s4, 0x80
	s_cbranch_scc0 .LBB0_216

; __global__ void __launch_bounds__(NWAVES * 64) fwd_kernel(Args args) {
	.amdhsa_kernel _Z10fwd_kernel4Args
		.amdhsa_group_segment_fixed_size 0
		.amdhsa_private_segment_fixed_size 0
		.amdhsa_kernarg_size 416
		.amdhsa_user_sgpr_count 2
		.amdhsa_user_sgpr_dispatch_ptr 0
		.amdhsa_user_sgpr_queue_ptr 0
		.amdhsa_user_sgpr_kernarg_segment_ptr 1
		.amdhsa_user_sgpr_dispatch_id 0
		.amdhsa_user_sgpr_kernarg_preload_length 0
		.amdhsa_user_sgpr_kernarg_preload_offset 0
		.amdhsa_user_sgpr_private_segment_size 0
		.amdhsa_uses_dynamic_stack 0
		.amdhsa_enable_private_segment 0
		.amdhsa_system_sgpr_workgroup_id_x 1
		.amdhsa_system_sgpr_workgroup_id_y 0
		.amdhsa_system_sgpr_workgroup_id_z 0
		.amdhsa_system_sgpr_workgroup_info 0
		.amdhsa_system_vgpr_workitem_id 2
		.amdhsa_next_free_vgpr 256
		.amdhsa_next_free_sgpr 101
		.amdhsa_accum_offset 256
		.amdhsa_reserve_vcc 1
		.amdhsa_float_round_mode_32 0
		.amdhsa_float_round_mode_16_64 0
		.amdhsa_float_denorm_mode_32 3
		.amdhsa_float_denorm_mode_16_64 3
		.amdhsa_dx10_clamp 1
		.amdhsa_ieee_mode 1
		.amdhsa_fp16_overflow 0
		.amdhsa_tg_split 0
		.amdhsa_exception_fp_ieee_invalid_op 0
		.amdhsa_exception_fp_denorm_src 0
		.amdhsa_exception_fp_ieee_div_zero 0
		.amdhsa_exception_fp_ieee_overflow 0
		.amdhsa_exception_fp_ieee_underflow 0
		.amdhsa_exception_fp_ieee_inexact 0
		.amdhsa_exception_int_div_zero 0
	.end_amdhsa_kernel

; __global__ void __launch_bounds__(NWAVES * 64) fwd_kernel(Args args) {
amdhsa.kernels:
  - .agpr_count:     0
    .args:
      - .offset:         0
        .size:           160
        .value_kind:     by_value
      - .offset:         160
        .size:           4
        .value_kind:     hidden_block_count_x
      - .offset:         164
        .size:           4
        .value_kind:     hidden_block_count_y
      - .offset:         168
        .size:           4
        .value_kind:     hidden_block_count_z
      - .offset:         172
        .size:           2
        .value_kind:     hidden_group_size_x
      - .offset:         174
        .size:           2
        .value_kind:     hidden_group_size_y
      - .offset:         176
        .size:           2
        .value_kind:     hidden_group_size_z
      - .offset:         178
        .size:           2
        .value_kind:     hidden_remainder_x
      - .offset:         180
        .size:           2
        .value_kind:     hidden_remainder_y
      - .offset:         182
        .size:           2
        .value_kind:     hidden_remainder_z
      - .offset:         200
        .size:           8
        .value_kind:     hidden_global_offset_x
      - .offset:         208
        .size:           8
        .value_kind:     hidden_global_offset_y
      - .offset:         216
        .size:           8
        .value_kind:     hidden_global_offset_z
      - .offset:         224
        .size:           2
        .value_kind:     hidden_grid_dims
      - .offset:         248
        .size:           8
        .value_kind:     hidden_multigrid_sync_arg
      - .offset:         280
        .size:           4
        .value_kind:     hidden_dynamic_lds_size
    .group_segment_fixed_size: 0
    .kernarg_segment_align: 8
    .kernarg_segment_size: 416
    .language:       OpenCL C
    .language_version:
      - 2
      - 0
    .max_flat_workgroup_size: 512
    .name:           _Z10fwd_kernel4Args
    .private_segment_fixed_size: 0
    .sgpr_count:     107
    .sgpr_spill_count: 164
    .symbol:         _Z10fwd_kernel4Args.kd
    .uniform_work_group_size: 1
    .uses_dynamic_stack: false
    .vgpr_count:     256
    .vgpr_spill_count: 0
    .wavefront_size: 64
